# residual epilogues (x += acc) of the resid-out and down GEMMs with all 16 loads of a thread in flight instead of one at a time
# baseline (speedup 1.0000x reference)
.LBB0_48:
	v_mov_b32_e32 v0, v163
	s_waitcnt vmcnt(7)
	v_mov_b32_e32 v35, v163
	v_lshlrev_b32_e32 v36, 7, v136
	v_ashrrev_i32_e32 v34, 1, v35
	v_and_b32_e32 v34, 0xffffffc0, v34
	v_lshl_add_u32 v34, v135, 7, v34
	v_and_or_b32 v34, v0, 15, v34
	v_lshrrev_b32_e32 v0, 2, v0
	v_and_b32_e32 v35, 64, v35
	v_and_b32_e32 v0, 12, v0
	v_or3_b32 v36, v35, v36, v0
	v_ashrrev_i32_e32 v35, 31, v34
	s_waitcnt vmcnt(6)
	v_lshlrev_b64 v[38:39], 12, v[34:35]
	v_ashrrev_i32_e32 v37, 31, v36
	v_lshl_add_u64 v[38:39], s[44:45], 0, v[38:39]
	v_lshlrev_b64 v[36:37], 2, v[36:37]
	s_waitcnt vmcnt(5)
	v_lshl_add_u64 v[46:47], v[38:39], 0, v[36:37]
	v_add_co_u32_e32 v38, vcc, 0x10000, v46
	s_nop 1
	v_addc_co_u32_e32 v39, vcc, 0, v47, vcc
	v_add_co_u32_e32 v40, vcc, 0x20000, v46
	s_nop 1
	v_addc_co_u32_e32 v41, vcc, 0, v47, vcc
	v_add_co_u32_e32 v48, vcc, 0x30000, v46
	s_nop 1
	v_addc_co_u32_e32 v49, vcc, 0, v47, vcc
	global_load_dwordx4 v[98:101], v[46:47], off
	global_load_dwordx4 v[102:105], v[46:47], off offset:64
	global_load_dwordx4 v[106:109], v[46:47], off offset:128
	global_load_dwordx4 v[110:113], v[46:47], off offset:192
	global_load_dwordx4 v[114:117], v[38:39], off
	global_load_dwordx4 v[118:121], v[38:39], off offset:64
	global_load_dwordx4 v[122:125], v[38:39], off offset:128
	global_load_dwordx4 v[126:129], v[38:39], off offset:192
	global_load_dwordx4 v[138:141], v[40:41], off
	global_load_dwordx4 v[142:145], v[40:41], off offset:64
	global_load_dwordx4 v[146:149], v[40:41], off offset:128
	global_load_dwordx4 v[150:153], v[40:41], off offset:192
	global_load_dwordx4 v[154:157], v[48:49], off
	global_load_dwordx4 v[158:161], v[48:49], off offset:64
	global_load_dwordx4 v[182:185], v[48:49], off offset:128
	global_load_dwordx4 v[186:189], v[48:49], off offset:192
	s_waitcnt vmcnt(15)
	v_add_f32_e32 v98, v94, v98
	v_add_f32_e32 v99, v95, v99
	v_add_f32_e32 v100, v96, v100
	v_add_f32_e32 v101, v97, v101
	global_store_dwordx4 v[46:47], v[98:101], off
	s_waitcnt vmcnt(15)
	v_add_f32_e32 v102, v90, v102
	v_add_f32_e32 v103, v91, v103
	v_add_f32_e32 v104, v92, v104
	v_add_f32_e32 v105, v93, v105
	global_store_dwordx4 v[46:47], v[102:105], off offset:64
	s_waitcnt vmcnt(15)
	v_add_f32_e32 v106, v86, v106
	v_add_f32_e32 v107, v87, v107
	v_add_f32_e32 v108, v88, v108
	v_add_f32_e32 v109, v89, v109
	global_store_dwordx4 v[46:47], v[106:109], off offset:128
	s_waitcnt vmcnt(15)
	v_add_f32_e32 v110, v82, v110
	v_add_f32_e32 v111, v83, v111
	v_add_f32_e32 v112, v84, v112
	v_add_f32_e32 v113, v85, v113
	global_store_dwordx4 v[46:47], v[110:113], off offset:192
	s_waitcnt vmcnt(15)
	v_add_f32_e32 v114, v74, v114
	v_add_f32_e32 v115, v75, v115
	v_add_f32_e32 v116, v76, v116
	v_add_f32_e32 v117, v77, v117
	global_store_dwordx4 v[38:39], v[114:117], off
	s_waitcnt vmcnt(15)
	v_add_f32_e32 v118, v70, v118
	v_add_f32_e32 v119, v71, v119
	v_add_f32_e32 v120, v72, v120
	v_add_f32_e32 v121, v73, v121
	global_store_dwordx4 v[38:39], v[118:121], off offset:64
	s_waitcnt vmcnt(15)
	v_add_f32_e32 v122, v58, v122
	v_add_f32_e32 v123, v59, v123
	v_add_f32_e32 v124, v60, v124
	v_add_f32_e32 v125, v61, v125
	global_store_dwordx4 v[38:39], v[122:125], off offset:128
	s_waitcnt vmcnt(15)
	v_add_f32_e32 v126, v42, v126
	v_add_f32_e32 v127, v43, v127
	v_add_f32_e32 v128, v44, v128
	v_add_f32_e32 v129, v45, v129
	global_store_dwordx4 v[38:39], v[126:129], off offset:192
	s_waitcnt vmcnt(15)
	v_add_f32_e32 v138, v30, v138
	v_add_f32_e32 v139, v31, v139
	v_add_f32_e32 v140, v32, v140
	v_add_f32_e32 v141, v33, v141
	global_store_dwordx4 v[40:41], v[138:141], off
	s_waitcnt vmcnt(15)
	v_add_f32_e32 v142, v26, v142
	v_add_f32_e32 v143, v27, v143
	v_add_f32_e32 v144, v28, v144
	v_add_f32_e32 v145, v29, v145
	global_store_dwordx4 v[40:41], v[142:145], off offset:64
	s_waitcnt vmcnt(15)
	v_add_f32_e32 v146, v22, v146
	v_add_f32_e32 v147, v23, v147
	v_add_f32_e32 v148, v24, v148
	v_add_f32_e32 v149, v25, v149
	global_store_dwordx4 v[40:41], v[146:149], off offset:128
	s_waitcnt vmcnt(15)
	v_add_f32_e32 v150, v18, v150
	v_add_f32_e32 v151, v19, v151
	v_add_f32_e32 v152, v20, v152
	v_add_f32_e32 v153, v21, v153
	global_store_dwordx4 v[40:41], v[150:153], off offset:192
	s_waitcnt vmcnt(15)
	v_add_f32_e32 v154, v14, v154
	v_add_f32_e32 v155, v15, v155
	v_add_f32_e32 v156, v16, v156
	v_add_f32_e32 v157, v17, v157
	global_store_dwordx4 v[48:49], v[154:157], off
	s_waitcnt vmcnt(15)
	v_add_f32_e32 v158, v10, v158
	v_add_f32_e32 v159, v11, v159
	v_add_f32_e32 v160, v12, v160
	v_add_f32_e32 v161, v13, v161
	global_store_dwordx4 v[48:49], v[158:161], off offset:64
	s_waitcnt vmcnt(15)
	v_add_f32_e32 v182, v6, v182
	v_add_f32_e32 v183, v7, v183
	v_add_f32_e32 v184, v8, v184
	v_add_f32_e32 v185, v9, v185
	global_store_dwordx4 v[48:49], v[182:185], off offset:128
	s_waitcnt vmcnt(15)
	v_add_f32_e32 v186, v2, v186
	v_add_f32_e32 v187, v3, v187
	v_add_f32_e32 v188, v4, v188
	v_add_f32_e32 v189, v5, v189
	global_store_dwordx4 v[48:49], v[186:189], off offset:192
	global_load_dword v0, v[164:165], off
	s_waitcnt vmcnt(0)
	v_add_u32_e32 v134, v0, v134
	v_cmp_lt_i32_e32 vcc, s36, v134
	s_or_b64 s[0:1], vcc, s[0:1]
	s_andn2_b64 exec, exec, s[0:1]
	s_cbranch_execz .LBB0_52
